# plus: hgrn chunk-image copy-out stores made write-through (sc0 sc1) so the prep-to-scan release writes back little
# baseline (speedup 1.0000x reference)
; #define LAS __attribute__((address_space(3)))
; __device__ __forceinline__ void hgrn_prep(const Params& p, LAS unsigned char* lds, int vb, int nb) {
;     ...
;         unsigned char* img = p.ws + WS_HIMG + (size_t)idx * HIMG_BYTES;
; #pragma unroll
;         for (int e = 0; e < 2; ++e) { const int id = tid + 512 * e; const int kr = id >> 3, part = id & 7;
;             if (lat) *(u32x4*)(img + HIMG_QD + id * 16) = *(const LAS u32x4*)(lds + H_QD + kr * HP + 16 * part);
;             *(u32x4*)(img + HIMG_KD + id * 16) = *(const LAS u32x4*)(lds + H_KD + kr * HP + 16 * part); }
;         if (lat) *(u32x4*)(img + HIMG_P + tid * 16) = *(const LAS u32x4*)(lds + H_P + (tid >> 3) * PP + 16 * (tid & 7));
;         if (tid < 32) *(u32x4*)(img + HIMG_D + tid * 16) = *(const LAS u32x4*)(lds + H_D + 16 * tid);
.LBB0_374:
	s_mul_i32 s41, s74, 0xa200
	s_mul_hi_i32 s40, s74, 0xa200
	s_add_u32 s68, s43, s41
	s_addc_u32 s69, s44, s40
	s_add_u32 s66, s68, 0x4000
	s_addc_u32 s67, s69, 0
	s_mov_b64 s[70:71], -1
	s_and_b64 vcc, exec, s[64:65]
	v_add_u32_e32 v29, v79, v88
	v_lshl_add_u64 v[40:41], s[66:67], 0, v[32:33]
	s_cbranch_vccz .LBB0_376
	ds_read_b128 v[42:45], v29
	s_mov_b64 s[70:71], 0
	s_waitcnt lgkmcnt(0)
	global_store_dwordx4 v[40:41], v[42:45], off sc0 sc1
.LBB0_376:
	s_andn2_b64 vcc, exec, s[70:71]
	v_lshl_add_u64 v[38:39], s[68:69], 0, v[32:33]
	s_cbranch_vccnz .LBB0_378
	v_add_u32_e32 v30, v80, v88
	ds_read_b128 v[42:45], v29
	ds_read_b128 v[106:109], v30 offset:61440
	v_add_u32_e32 v29, v80, v89
	ds_read_b128 v[110:113], v29 offset:61440
	s_waitcnt lgkmcnt(2)
	global_store_dwordx4 v[40:41], v[42:45], off sc0 sc1
	s_waitcnt lgkmcnt(1)
	global_store_dwordx4 v[38:39], v[106:109], off sc0 sc1
	v_lshl_add_u64 v[40:41], s[68:69], 0, v[34:35]
	s_waitcnt lgkmcnt(0)
	global_store_dwordx4 v[40:41], v[110:113], off sc0 sc1
.LBB0_378:
	v_add_u32_e32 v29, v79, v89
	ds_read_b128 v[40:43], v29
	v_lshl_add_u64 v[44:45], s[66:67], 0, v[34:35]
	s_andn2_b64 vcc, exec, s[36:37]
	s_waitcnt lgkmcnt(0)
	global_store_dwordx4 v[44:45], v[40:43], off sc0 sc1
	s_cbranch_vccnz .LBB0_380
	ds_read_b128 v[40:43], v104
	v_add_co_u32_e32 v44, vcc, 0x8000, v38
	s_nop 1
	v_addc_co_u32_e32 v45, vcc, 0, v39, vcc
	s_waitcnt lgkmcnt(0)
	global_store_dwordx4 v[44:45], v[40:43], off sc0 sc1
.LBB0_380:
	s_and_saveexec_b64 s[36:37], s[22:23]
	s_cbranch_execz .LBB0_341
	v_add_u32_e32 v29, 0, v32
	v_add_u32_e32 v29, 0x1ec00, v29
	ds_read_b128 v[40:43], v29
	v_add_co_u32_e32 v38, vcc, 0xa000, v38
	s_nop 1
	v_addc_co_u32_e32 v39, vcc, 0, v39, vcc
	s_waitcnt lgkmcnt(0)
	global_store_dwordx4 v[38:39], v[40:43], off sc0 sc1
	s_branch .LBB0_341
